# v6: sgu de-serialised, pgemm odd-WG 6us stagger, isel early key loads
# speedup vs baseline: 1.0308x; 1.0050x over previous
.LBB0_325:
	v_readfirstlane_b32 s0, v21
	global_load_dwordx4 v[48:51], v[22:23], off
	global_load_dwordx4 v[52:55], v[22:23], off offset:32
	global_load_dwordx4 v[56:59], v[22:23], off offset:64
	global_load_dwordx4 v[60:63], v[22:23], off offset:96
	global_load_dwordx4 v[64:67], v[22:23], off offset:128
	global_load_dwordx4 v[68:71], v[22:23], off offset:160
	global_load_dwordx4 v[72:75], v[22:23], off offset:192
	global_load_dwordx4 v[76:79], v[22:23], off offset:224
	ds_read_b128 v[80:83], v27
	ds_read_b128 v[84:87], v27 offset:32
	ds_read_b128 v[88:91], v27 offset:64
	ds_read_b128 v[92:95], v27 offset:96
	ds_read_b128 v[96:99], v27 offset:128
	ds_read_b128 v[100:103], v27 offset:160
	ds_read_b128 v[104:107], v27 offset:192
	ds_read_b128 v[108:111], v27 offset:224
	s_waitcnt vmcnt(6) lgkmcnt(6)
	v_mfma_f32_32x32x16_bf16 v[2:17], v[80:83], v[48:51], v[2:17]
	v_mfma_f32_32x32x16_bf16 v[2:17], v[84:87], v[52:55], v[2:17]
	s_cmp_lt_u32 s0, 4
	s_cbranch_scc1 .Lsgu_done0
	s_waitcnt vmcnt(4) lgkmcnt(4)
	v_mfma_f32_32x32x16_bf16 v[2:17], v[88:91], v[56:59], v[2:17]
	v_mfma_f32_32x32x16_bf16 v[2:17], v[92:95], v[60:63], v[2:17]
	s_cmp_lt_u32 s0, 6
	s_cbranch_scc1 .Lsgu_done0
	s_waitcnt vmcnt(2) lgkmcnt(2)
	v_mfma_f32_32x32x16_bf16 v[2:17], v[96:99], v[64:67], v[2:17]
	v_mfma_f32_32x32x16_bf16 v[2:17], v[100:103], v[68:71], v[2:17]
	s_cmp_lt_u32 s0, 8
	s_cbranch_scc1 .Lsgu_done0
	s_waitcnt vmcnt(0) lgkmcnt(0)
	v_mfma_f32_32x32x16_bf16 v[2:17], v[104:107], v[72:75], v[2:17]
	v_mfma_f32_32x32x16_bf16 v[2:17], v[108:111], v[76:79], v[2:17]
.Lsgu_done0:
	v_or_b32_e32 v0, s3, v24
	v_lshlrev_b32_e32 v22, 5, v35
	v_lshrrev_b32_e32 v0, 3, v0
	v_and_b32_e32 v22, 0xffffffc0, v22
	v_and_b32_e32 v33, 30, v0
	v_add_u32_e32 v0, s5, v22
	v_ashrrev_i32_e32 v22, 8, v0
	v_lshlrev_b32_e32 v23, 5, v25
	v_add_u32_e32 v22, s4, v22
	v_lshlrev_b32_e32 v31, 1, v25
	v_lshlrev_b32_e32 v30, 2, v26
	v_and_b32_e32 v32, 0x1e0, v23
	v_ashrrev_i32_e32 v23, 31, v22
	v_lshrrev_b32_e32 v25, 7, v0
	v_lshlrev_b32_e32 v26, 9, v35
	v_and_or_b32 v25, v25, 1, v33
	v_and_b32_e32 v26, 0x400, v26
	v_lshlrev_b64 v[22:23], 17, v[22:23]
	v_lshl_or_b32 v25, v25, 11, v26
	v_lshl_add_u64 v[26:27], s[70:71], 0, v[22:23]
	v_add_u32_e32 v22, 0x800, v0
	v_ashrrev_i32_e32 v22, 8, v22
	v_add_u32_e32 v22, s4, v22
	v_ashrrev_i32_e32 v23, 31, v22
	v_lshlrev_b64 v[22:23], 17, v[22:23]
	v_lshl_add_u64 v[40:41], s[70:71], 0, v[22:23]
	v_ashrrev_i32_e32 v22, 6, v0
	v_lshlrev_b32_e32 v0, 6, v24
	v_and_b32_e32 v29, 0x1c00, v0
	v_or3_b32 v0, v25, v32, v30
	v_lshlrev_b32_e32 v0, 1, v0
	v_lshl_add_u64 v[24:25], v[26:27], 0, v[0:1]
	v_lshl_add_u64 v[26:27], v[40:41], 0, v[0:1]
	global_load_dwordx2 v[112:113], v[24:25], off
	global_load_dwordx2 v[114:115], v[26:27], off
	global_load_dwordx2 v[116:117], v[24:25], off offset:16
	global_load_dwordx2 v[118:119], v[26:27], off offset:16
	global_load_dwordx2 v[120:121], v[24:25], off offset:32
	global_load_dwordx2 v[122:123], v[26:27], off offset:32
	global_load_dwordx2 v[124:125], v[24:25], off offset:48
	global_load_dwordx2 v[126:127], v[26:27], off offset:48
	v_add_f32_e32 v44, v28, v2
	v_add_f32_e32 v2, v28, v3
	v_and_b32_e32 v38, 16, v31
	s_lshl_b32 s0, s2, 11
	s_and_b32 s72, s45, 0x3f0
	s_and_b32 s0, s0, 0x4000
	v_ashrrev_i32_e32 v23, 31, v22
	s_add_u32 s0, s61, s0
	v_readlane_b32 s1, v238, 22
	v_lshl_add_u64 v[22:23], v[22:23], 0, s[72:73]
	s_addc_u32 s1, s1, 0
	v_lshlrev_b64 v[22:23], 15, v[22:23]
	v_lshl_add_u64 v[22:23], s[0:1], 0, v[22:23]
	s_movk_i32 s2, 0x2200
	s_waitcnt vmcnt(7)
	v_mov_b32_e32 v42, v112
	v_mov_b32_e32 v43, v113
	v_lshlrev_b32_e32 v46, 16, v42
	s_waitcnt vmcnt(6)
	v_mov_b32_e32 v40, v114
	v_mov_b32_e32 v41, v115
	v_lshlrev_b32_e32 v47, 16, v40
	v_mul_f32_e32 v0, 0xbfb8aa3b, v47
	v_exp_f32_e32 v0, v0
	s_nop 0
	v_add_f32_e32 v0, 1.0, v0
	v_rcp_f32_e32 v45, v0
	s_nop 0
	v_pk_mul_f32 v[44:45], v[44:45], v[46:47]
	s_nop 0
	v_mul_f32_e32 v0, v44, v45
	v_and_b32_e32 v45, 0xffff0000, v40
	v_mul_f32_e32 v3, 0xbfb8aa3b, v45
	v_exp_f32_e32 v3, v3
	v_and_b32_e32 v44, 0xffff0000, v42
	v_add_f32_e32 v42, v28, v6
	v_add_f32_e32 v6, v28, v7
	v_add_f32_e32 v3, 1.0, v3
	v_rcp_f32_e32 v3, v3
	s_nop 0
	v_pk_mul_f32 v[2:3], v[2:3], v[44:45]
	v_lshlrev_b32_e32 v45, 16, v41
	v_mul_f32_e32 v34, v2, v3
	v_mul_f32_e32 v3, 0xbfb8aa3b, v45
	v_exp_f32_e32 v3, v3
	v_add_f32_e32 v2, v28, v4
	v_lshlrev_b32_e32 v44, 16, v43
	v_and_b32_e32 v4, 0xffff0000, v43
	v_add_f32_e32 v3, 1.0, v3
	v_rcp_f32_e32 v3, v3
	s_nop 0
	v_pk_mul_f32 v[2:3], v[2:3], v[44:45]
	s_nop 0
	v_mul_f32_e32 v37, v2, v3
	v_add_f32_e32 v2, v28, v5
	v_and_b32_e32 v5, 0xffff0000, v41
	v_mul_f32_e32 v3, 0xbfb8aa3b, v5
	v_exp_f32_e32 v3, v3
	s_nop 0
	v_add_f32_e32 v3, 1.0, v3
	v_rcp_f32_e32 v3, v3
	s_nop 0
	v_pk_mul_f32 v[2:3], v[2:3], v[4:5]
	s_nop 0
	v_mul_f32_e32 v2, v2, v3
	v_cvt_pk_bf16_f32 v5, v37, v2
	v_or_b32_e32 v37, v38, v32
	v_cvt_pk_bf16_f32 v4, v0, v34
	v_or_b32_e32 v34, v37, v30
	v_or_b32_e32 v0, v29, v34
	v_lshlrev_b32_e32 v0, 1, v0
	v_lshl_add_u64 v[2:3], v[22:23], 0, v[0:1]
	global_store_dwordx2 v[2:3], v[4:5], off
	s_waitcnt vmcnt(6)
	v_mov_b32_e32 v4, v116
	v_mov_b32_e32 v5, v117
	v_lshlrev_b32_e32 v44, 16, v4
	s_waitcnt vmcnt(5)
	v_mov_b32_e32 v40, v118
	v_mov_b32_e32 v41, v119
	v_lshlrev_b32_e32 v45, 16, v40
	v_mul_f32_e32 v0, 0xbfb8aa3b, v45
	v_exp_f32_e32 v0, v0
	s_nop 0
	v_add_f32_e32 v0, 1.0, v0
	v_rcp_f32_e32 v43, v0
	s_nop 0
	v_pk_mul_f32 v[42:43], v[42:43], v[44:45]
	s_nop 0
	v_mul_f32_e32 v0, v42, v43
	v_and_b32_e32 v43, 0xffff0000, v40
	v_and_b32_e32 v42, 0xffff0000, v4
	v_mul_f32_e32 v4, 0xbfb8aa3b, v43
	v_exp_f32_e32 v4, v4
	s_nop 0
	v_add_f32_e32 v4, 1.0, v4
	v_rcp_f32_e32 v7, v4
	s_nop 0
	v_pk_mul_f32 v[6:7], v[6:7], v[42:43]
	v_lshlrev_b32_e32 v43, 16, v41
	v_mul_f32_e32 v4, 0xbfb8aa3b, v43
	v_exp_f32_e32 v4, v4
	v_mul_f32_e32 v39, v6, v7
	v_add_f32_e32 v6, v28, v8
	v_lshlrev_b32_e32 v42, 16, v5
	v_add_f32_e32 v4, 1.0, v4
	v_rcp_f32_e32 v7, v4
	v_add_f32_e32 v4, v28, v9
	v_pk_mul_f32 v[6:7], v[6:7], v[42:43]
	s_nop 0
	v_mul_f32_e32 v8, v6, v7
	v_and_b32_e32 v7, 0xffff0000, v41
	v_and_b32_e32 v6, 0xffff0000, v5
	v_mul_f32_e32 v5, 0xbfb8aa3b, v7
	v_exp_f32_e32 v5, v5
	s_nop 0
	v_add_f32_e32 v5, 1.0, v5
	v_rcp_f32_e32 v5, v5
	s_nop 0
	v_pk_mul_f32 v[4:5], v[4:5], v[6:7]
	s_nop 0
	v_mul_f32_e32 v5, v4, v5
	v_cvt_pk_bf16_f32 v4, v0, v39
	v_cvt_pk_bf16_f32 v5, v8, v5
	global_store_dwordx2 v[2:3], v[4:5], off offset:16
	v_add_f32_e32 v6, v28, v10
	s_waitcnt vmcnt(5)
	v_mov_b32_e32 v2, v120
	v_mov_b32_e32 v3, v121
	v_lshlrev_b32_e32 v8, 16, v2
	s_waitcnt vmcnt(4)
	v_mov_b32_e32 v4, v122
	v_mov_b32_e32 v5, v123
	v_lshlrev_b32_e32 v9, 16, v4
	v_mul_f32_e32 v0, 0xbfb8aa3b, v9
	v_exp_f32_e32 v0, v0
	s_nop 0
	v_add_f32_e32 v0, 1.0, v0
	v_rcp_f32_e32 v7, v0
	s_nop 0
	v_pk_mul_f32 v[6:7], v[6:7], v[8:9]
	v_and_b32_e32 v9, 0xffff0000, v4
	v_and_b32_e32 v8, 0xffff0000, v2
	v_mul_f32_e32 v2, 0xbfb8aa3b, v9
	v_exp_f32_e32 v2, v2
	v_mul_f32_e32 v0, v6, v7
	v_add_f32_e32 v6, v28, v11
	v_and_b32_e32 v4, 0xffff0000, v3
	v_add_f32_e32 v2, 1.0, v2
	v_rcp_f32_e32 v7, v2
	s_nop 0
	v_pk_mul_f32 v[6:7], v[6:7], v[8:9]
	v_lshlrev_b32_e32 v9, 16, v5
	v_and_b32_e32 v5, 0xffff0000, v5
	v_lshlrev_b32_e32 v8, 16, v3
	v_mul_f32_e32 v3, 0xbfb8aa3b, v5
	v_exp_f32_e32 v3, v3
	v_mul_f32_e32 v2, 0xbfb8aa3b, v9
	v_exp_f32_e32 v2, v2
	v_mul_f32_e32 v10, v6, v7
	v_add_f32_e32 v3, 1.0, v3
	v_rcp_f32_e32 v3, v3
	v_add_f32_e32 v2, 1.0, v2
	v_rcp_f32_e32 v7, v2
	v_add_f32_e32 v2, v28, v13
	v_pk_mul_f32 v[2:3], v[2:3], v[4:5]
	v_add_f32_e32 v6, v28, v12
	v_mul_f32_e32 v3, v2, v3
	v_cvt_pk_bf16_f32 v2, v0, v10
	v_or_b32_e32 v10, v30, v32
	v_bitop3_b32 v31, v10, v31, 16 bitop3:0x72
	v_or_b32_e32 v0, v31, v29
	v_lshlrev_b32_e32 v0, 1, v0
	v_pk_mul_f32 v[6:7], v[6:7], v[8:9]
	v_lshl_add_u64 v[4:5], v[22:23], 0, v[0:1]
	v_mul_f32_e32 v6, v6, v7
	v_cvt_pk_bf16_f32 v3, v6, v3
	global_store_dwordx2 v[4:5], v[2:3], off
	v_add_f32_e32 v6, v28, v14
	v_bitop3_b32 v24, v10, v38, 24 bitop3:0x36
	s_waitcnt vmcnt(4)
	v_mov_b32_e32 v2, v124
	v_mov_b32_e32 v3, v125
	v_lshlrev_b32_e32 v8, 16, v2
	s_waitcnt vmcnt(3)
	v_mov_b32_e32 v4, v126
	v_mov_b32_e32 v5, v127
	v_lshlrev_b32_e32 v9, 16, v4
	v_mul_f32_e32 v0, 0xbfb8aa3b, v9
	v_exp_f32_e32 v0, v0
	s_nop 0
	v_add_f32_e32 v0, 1.0, v0
	v_rcp_f32_e32 v7, v0
	s_nop 0
	v_pk_mul_f32 v[6:7], v[6:7], v[8:9]
	v_and_b32_e32 v9, 0xffff0000, v4
	v_and_b32_e32 v8, 0xffff0000, v2
	v_mul_f32_e32 v2, 0xbfb8aa3b, v9
	v_exp_f32_e32 v2, v2
	v_mul_f32_e32 v0, v6, v7
	v_add_f32_e32 v6, v28, v15
	v_and_b32_e32 v4, 0xffff0000, v3
	v_add_f32_e32 v2, 1.0, v2
	v_rcp_f32_e32 v7, v2
	s_nop 0
	v_pk_mul_f32 v[6:7], v[6:7], v[8:9]
	v_lshlrev_b32_e32 v9, 16, v5
	v_and_b32_e32 v5, 0xffff0000, v5
	v_lshlrev_b32_e32 v8, 16, v3
	v_mul_f32_e32 v3, 0xbfb8aa3b, v5
	v_exp_f32_e32 v3, v3
	v_mul_f32_e32 v2, 0xbfb8aa3b, v9
	v_exp_f32_e32 v2, v2
	v_mul_f32_e32 v11, v6, v7
	v_add_f32_e32 v3, 1.0, v3
	v_rcp_f32_e32 v3, v3
	v_add_f32_e32 v2, 1.0, v2
	v_rcp_f32_e32 v7, v2
	v_add_f32_e32 v2, v28, v17
	v_pk_mul_f32 v[2:3], v[2:3], v[4:5]
	v_add_f32_e32 v6, v28, v16
	v_mul_f32_e32 v3, v2, v3
	v_cvt_pk_bf16_f32 v2, v0, v11
	v_or_b32_e32 v0, v24, v29
	v_pk_mul_f32 v[6:7], v[6:7], v[8:9]
	v_lshlrev_b32_e32 v0, 1, v0
	v_mul_f32_e32 v6, v6, v7
	v_cvt_pk_bf16_f32 v3, v6, v3
	v_lshl_add_u64 v[4:5], v[22:23], 0, v[0:1]
	v_or_b32_e32 v0, 1, v35
	global_store_dwordx2 v[4:5], v[2:3], off
	v_mad_u64_u32 v[2:3], s[2:3], v0, s2, v[20:21]
	v_add3_u32 v20, v2, v36, 0
	v_mov_b32_e32 v2, 0
	s_mov_b64 s[2:3], 0
	v_mov_b32_e32 v3, v2
	v_mov_b32_e32 v4, v2
	v_mov_b32_e32 v5, v2
	v_mov_b32_e32 v6, v2
	v_mov_b32_e32 v7, v2
	v_mov_b32_e32 v8, v2
	v_mov_b32_e32 v9, v2
	v_mov_b32_e32 v10, v2
	v_mov_b32_e32 v11, v2
	v_mov_b32_e32 v12, v2
	v_mov_b32_e32 v13, v2
	v_mov_b32_e32 v14, v2
	v_mov_b32_e32 v15, v2
	v_mov_b32_e32 v16, v2
	v_mov_b32_e32 v17, v2
.LBB0_327:
	v_readfirstlane_b32 s2, v21
	global_load_dwordx4 v[48:51], v[18:19], off
	global_load_dwordx4 v[52:55], v[18:19], off offset:32
	global_load_dwordx4 v[56:59], v[18:19], off offset:64
	global_load_dwordx4 v[60:63], v[18:19], off offset:96
	global_load_dwordx4 v[64:67], v[18:19], off offset:128
	global_load_dwordx4 v[68:71], v[18:19], off offset:160
	global_load_dwordx4 v[72:75], v[18:19], off offset:192
	global_load_dwordx4 v[76:79], v[18:19], off offset:224
	ds_read_b128 v[80:83], v20
	ds_read_b128 v[84:87], v20 offset:32
	ds_read_b128 v[88:91], v20 offset:64
	ds_read_b128 v[92:95], v20 offset:96
	ds_read_b128 v[96:99], v20 offset:128
	ds_read_b128 v[100:103], v20 offset:160
	ds_read_b128 v[104:107], v20 offset:192
	ds_read_b128 v[108:111], v20 offset:224
	s_waitcnt vmcnt(6) lgkmcnt(6)
	v_mfma_f32_32x32x16_bf16 v[2:17], v[80:83], v[48:51], v[2:17]
	v_mfma_f32_32x32x16_bf16 v[2:17], v[84:87], v[52:55], v[2:17]
	s_cmp_lt_u32 s2, 4
	s_cbranch_scc1 .Lsgu_done1
	s_waitcnt vmcnt(4) lgkmcnt(4)
	v_mfma_f32_32x32x16_bf16 v[2:17], v[88:91], v[56:59], v[2:17]
	v_mfma_f32_32x32x16_bf16 v[2:17], v[92:95], v[60:63], v[2:17]
	s_cmp_lt_u32 s2, 6
	s_cbranch_scc1 .Lsgu_done1
	s_waitcnt vmcnt(2) lgkmcnt(2)
	v_mfma_f32_32x32x16_bf16 v[2:17], v[96:99], v[64:67], v[2:17]
	v_mfma_f32_32x32x16_bf16 v[2:17], v[100:103], v[68:71], v[2:17]
	s_cmp_lt_u32 s2, 8
	s_cbranch_scc1 .Lsgu_done1
	s_waitcnt vmcnt(0) lgkmcnt(0)
	v_mfma_f32_32x32x16_bf16 v[2:17], v[104:107], v[72:75], v[2:17]
	v_mfma_f32_32x32x16_bf16 v[2:17], v[108:111], v[76:79], v[2:17]
.Lsgu_done1:
	v_lshl_add_u32 v26, v0, 5, s5
	v_lshrrev_b32_e32 v20, 7, v26
	v_ashrrev_i32_e32 v18, 8, v26
	v_and_or_b32 v20, v20, 1, v33
	v_lshlrev_b32_e32 v0, 9, v0
	v_add_u32_e32 v18, s4, v18
	v_lshlrev_b32_e32 v20, 11, v20
	v_and_b32_e32 v0, 0x600, v0
	v_ashrrev_i32_e32 v19, 31, v18
	v_or3_b32 v35, v20, v0, v32
	v_add_u32_e32 v0, 0x800, v26
	v_lshlrev_b64 v[18:19], 17, v[18:19]
	v_ashrrev_i32_e32 v0, 8, v0
	v_lshl_add_u64 v[20:21], s[70:71], 0, v[18:19]
	v_add_u32_e32 v18, s4, v0
	v_ashrrev_i32_e32 v19, 31, v18
	v_lshlrev_b64 v[18:19], 17, v[18:19]
	v_or_b32_e32 v0, v35, v30
	v_lshl_add_u64 v[22:23], s[70:71], 0, v[18:19]
	v_lshlrev_b32_e32 v0, 1, v0
	v_ashrrev_i32_e32 v18, 6, v26
	v_lshl_add_u64 v[26:27], v[20:21], 0, v[0:1]
	v_lshl_add_u64 v[32:33], v[22:23], 0, v[0:1]
	v_or3_b32 v25, v30, v37, 8
	global_load_dwordx2 v[128:129], v[26:27], off
	global_load_dwordx2 v[130:131], v[32:33], off
	global_load_dwordx2 v[132:133], v[26:27], off offset:16
	global_load_dwordx2 v[134:135], v[32:33], off offset:16
	global_load_dwordx2 v[136:137], v[26:27], off offset:32
	global_load_dwordx2 v[138:139], v[32:33], off offset:32
	global_load_dwordx2 v[140:141], v[26:27], off offset:48
	global_load_dwordx2 v[142:143], v[32:33], off offset:48
	v_add_f32_e32 v36, v28, v2
	v_add_f32_e32 v2, v28, v3
	v_ashrrev_i32_e32 v19, 31, v18
	v_lshl_add_u64 v[18:19], v[18:19], 0, s[72:73]
	v_lshlrev_b64 v[18:19], 15, v[18:19]
	v_lshl_add_u64 v[18:19], s[0:1], 0, v[18:19]
	s_waitcnt vmcnt(7)
	v_mov_b32_e32 v26, v128
	v_mov_b32_e32 v27, v129
	v_lshlrev_b32_e32 v38, 16, v26
	s_waitcnt vmcnt(6)
	v_mov_b32_e32 v32, v130
	v_mov_b32_e32 v33, v131
	v_lshlrev_b32_e32 v39, 16, v32
	v_mul_f32_e32 v0, 0xbfb8aa3b, v39
	v_exp_f32_e32 v0, v0
	s_nop 0
	v_add_f32_e32 v0, 1.0, v0
	v_rcp_f32_e32 v37, v0
	s_nop 0
	v_pk_mul_f32 v[36:37], v[36:37], v[38:39]
	s_nop 0
	v_mul_f32_e32 v0, v36, v37
	v_and_b32_e32 v37, 0xffff0000, v32
	v_mul_f32_e32 v3, 0xbfb8aa3b, v37
	v_exp_f32_e32 v3, v3
	v_and_b32_e32 v36, 0xffff0000, v26
	v_add_f32_e32 v3, 1.0, v3
	v_rcp_f32_e32 v3, v3
	s_nop 0
	v_pk_mul_f32 v[2:3], v[2:3], v[36:37]
	v_lshlrev_b32_e32 v37, 16, v33
	v_mul_f32_e32 v26, v2, v3
	v_mul_f32_e32 v3, 0xbfb8aa3b, v37
	v_exp_f32_e32 v3, v3
	v_add_f32_e32 v2, v28, v4
	v_lshlrev_b32_e32 v36, 16, v27
	v_and_b32_e32 v4, 0xffff0000, v27
	v_add_f32_e32 v3, 1.0, v3
	v_rcp_f32_e32 v3, v3
	s_nop 0
	v_pk_mul_f32 v[2:3], v[2:3], v[36:37]
	s_nop 0
	v_mul_f32_e32 v32, v2, v3
	v_add_f32_e32 v2, v28, v5
	v_and_b32_e32 v5, 0xffff0000, v33
	v_mul_f32_e32 v3, 0xbfb8aa3b, v5
	v_exp_f32_e32 v3, v3
	s_nop 0
	v_add_f32_e32 v3, 1.0, v3
	v_rcp_f32_e32 v3, v3
	s_nop 0
	v_pk_mul_f32 v[2:3], v[2:3], v[4:5]
	s_nop 0
	v_mul_f32_e32 v3, v2, v3
	v_cvt_pk_bf16_f32 v2, v0, v26
	v_add_lshl_u32 v0, v29, v34, 1
	v_cvt_pk_bf16_f32 v3, v32, v3
	v_lshl_add_u64 v[4:5], v[18:19], 0, v[0:1]
	v_add_lshl_u32 v0, v35, v30, 1
	global_store_dwordx2 v[4:5], v[2:3], off offset:1024
	v_lshl_add_u64 v[2:3], v[20:21], 0, v[0:1]
	v_lshl_add_u64 v[4:5], v[22:23], 0, v[0:1]
	v_add_f32_e32 v26, v28, v6
	v_add_f32_e32 v6, v28, v7
	s_waitcnt vmcnt(6)
	v_mov_b32_e32 v20, v132
	v_mov_b32_e32 v21, v133
	v_lshlrev_b32_e32 v32, 16, v20
	s_waitcnt vmcnt(5)
	v_mov_b32_e32 v22, v134
	v_mov_b32_e32 v23, v135
	v_lshlrev_b32_e32 v33, 16, v22
	v_mul_f32_e32 v0, 0xbfb8aa3b, v33
	v_exp_f32_e32 v0, v0
	s_nop 0
	v_add_f32_e32 v0, 1.0, v0
	v_rcp_f32_e32 v27, v0
	s_nop 0
	v_pk_mul_f32 v[26:27], v[26:27], v[32:33]
	s_nop 0
	v_mul_f32_e32 v0, v26, v27
	v_and_b32_e32 v27, 0xffff0000, v22
	v_mul_f32_e32 v7, 0xbfb8aa3b, v27
	v_exp_f32_e32 v7, v7
	v_and_b32_e32 v26, 0xffff0000, v20
	v_add_f32_e32 v7, 1.0, v7
	v_rcp_f32_e32 v7, v7
	s_nop 0
	v_pk_mul_f32 v[6:7], v[6:7], v[26:27]
	v_lshlrev_b32_e32 v27, 16, v23
	v_mul_f32_e32 v20, v6, v7
	v_mul_f32_e32 v7, 0xbfb8aa3b, v27
	v_exp_f32_e32 v7, v7
	v_add_f32_e32 v6, v28, v8
	v_lshlrev_b32_e32 v26, 16, v21
	v_and_b32_e32 v8, 0xffff0000, v21
	v_add_f32_e32 v7, 1.0, v7
	v_rcp_f32_e32 v7, v7
	s_nop 0
	v_pk_mul_f32 v[6:7], v[6:7], v[26:27]
	s_nop 0
	v_mul_f32_e32 v22, v6, v7
	v_add_f32_e32 v6, v28, v9
	v_and_b32_e32 v9, 0xffff0000, v23
	v_mul_f32_e32 v7, 0xbfb8aa3b, v9
	v_exp_f32_e32 v7, v7
	s_nop 0
	v_add_f32_e32 v7, 1.0, v7
	v_rcp_f32_e32 v7, v7
	s_nop 0
	v_pk_mul_f32 v[6:7], v[6:7], v[8:9]
	s_nop 0
	v_mul_f32_e32 v7, v6, v7
	v_cvt_pk_bf16_f32 v6, v0, v20
	v_add_lshl_u32 v0, v29, v25, 1
	v_lshl_add_u64 v[8:9], v[18:19], 0, v[0:1]
	v_cvt_pk_bf16_f32 v7, v22, v7
	global_store_dwordx2 v[8:9], v[6:7], off offset:1024
	v_add_f32_e32 v20, v28, v10
	v_add_f32_e32 v10, v28, v11
	s_waitcnt vmcnt(5)
	v_mov_b32_e32 v6, v136
	v_mov_b32_e32 v7, v137
	v_lshlrev_b32_e32 v22, 16, v6
	s_waitcnt vmcnt(4)
	v_mov_b32_e32 v8, v138
	v_mov_b32_e32 v9, v139
	v_lshlrev_b32_e32 v23, 16, v8
	v_mul_f32_e32 v0, 0xbfb8aa3b, v23
	v_exp_f32_e32 v0, v0
	s_nop 0
	v_add_f32_e32 v0, 1.0, v0
	v_rcp_f32_e32 v21, v0
	s_nop 0
	v_pk_mul_f32 v[20:21], v[20:21], v[22:23]
	s_nop 0
	v_mul_f32_e32 v0, v20, v21
	v_and_b32_e32 v21, 0xffff0000, v8
	v_and_b32_e32 v20, 0xffff0000, v6
	v_mul_f32_e32 v6, 0xbfb8aa3b, v21
	v_exp_f32_e32 v6, v6
	v_and_b32_e32 v8, 0xffff0000, v7
	v_add_f32_e32 v6, 1.0, v6
	v_rcp_f32_e32 v11, v6
	s_nop 0
	v_pk_mul_f32 v[10:11], v[10:11], v[20:21]
	v_lshlrev_b32_e32 v21, 16, v9
	v_and_b32_e32 v9, 0xffff0000, v9
	v_lshlrev_b32_e32 v20, 16, v7
	v_mul_f32_e32 v7, 0xbfb8aa3b, v9
	v_exp_f32_e32 v7, v7
	v_mul_f32_e32 v6, 0xbfb8aa3b, v21
	v_exp_f32_e32 v6, v6
	v_mul_f32_e32 v22, v10, v11
	v_add_f32_e32 v7, 1.0, v7
	v_rcp_f32_e32 v7, v7
	v_add_f32_e32 v6, 1.0, v6
	v_rcp_f32_e32 v11, v6
	v_add_f32_e32 v6, v28, v13
	v_pk_mul_f32 v[6:7], v[6:7], v[8:9]
	v_add_f32_e32 v10, v28, v12
	v_mul_f32_e32 v7, v6, v7
	v_cvt_pk_bf16_f32 v6, v0, v22
	v_add_lshl_u32 v0, v29, v31, 1
	v_pk_mul_f32 v[10:11], v[10:11], v[20:21]
	v_lshl_add_u64 v[8:9], v[18:19], 0, v[0:1]
	v_mul_f32_e32 v10, v10, v11
	v_cvt_pk_bf16_f32 v7, v10, v7
	global_store_dwordx2 v[8:9], v[6:7], off offset:1024
	v_add_f32_e32 v6, v28, v14
	s_waitcnt vmcnt(4)
	v_mov_b32_e32 v2, v140
	v_mov_b32_e32 v3, v141
	v_lshlrev_b32_e32 v8, 16, v2
	s_waitcnt vmcnt(3)
	v_mov_b32_e32 v4, v142
	v_mov_b32_e32 v5, v143
	v_lshlrev_b32_e32 v9, 16, v4
	v_mul_f32_e32 v0, 0xbfb8aa3b, v9
	v_exp_f32_e32 v0, v0
	s_nop 0
	v_add_f32_e32 v0, 1.0, v0
	v_rcp_f32_e32 v7, v0
	s_nop 0
	v_pk_mul_f32 v[6:7], v[6:7], v[8:9]
	v_and_b32_e32 v9, 0xffff0000, v4
	v_and_b32_e32 v8, 0xffff0000, v2
	v_mul_f32_e32 v2, 0xbfb8aa3b, v9
	v_exp_f32_e32 v2, v2
	v_mul_f32_e32 v0, v6, v7
	v_add_f32_e32 v6, v28, v15
	v_and_b32_e32 v4, 0xffff0000, v3
	v_add_f32_e32 v2, 1.0, v2
	v_rcp_f32_e32 v7, v2
	s_nop 0
	v_pk_mul_f32 v[6:7], v[6:7], v[8:9]
	v_lshlrev_b32_e32 v9, 16, v5
	v_and_b32_e32 v5, 0xffff0000, v5
	v_lshlrev_b32_e32 v8, 16, v3
	v_mul_f32_e32 v3, 0xbfb8aa3b, v5
	v_exp_f32_e32 v3, v3
	v_mul_f32_e32 v2, 0xbfb8aa3b, v9
	v_exp_f32_e32 v2, v2
	v_mul_f32_e32 v10, v6, v7
	v_add_f32_e32 v3, 1.0, v3
	v_rcp_f32_e32 v3, v3
	v_add_f32_e32 v2, 1.0, v2
	v_rcp_f32_e32 v7, v2
	v_add_f32_e32 v2, v28, v17
	v_pk_mul_f32 v[2:3], v[2:3], v[4:5]
	v_add_f32_e32 v6, v28, v16
	v_mul_f32_e32 v3, v2, v3
	v_cvt_pk_bf16_f32 v2, v0, v10
	v_add_lshl_u32 v0, v29, v24, 1
	v_pk_mul_f32 v[6:7], v[6:7], v[8:9]
	v_lshl_add_u64 v[4:5], v[18:19], 0, v[0:1]
	v_mul_f32_e32 v6, v6, v7
	v_cvt_pk_bf16_f32 v3, v6, v3
	global_store_dwordx2 v[4:5], v[2:3], off offset:1024
	s_barrier

.LBB0_333:
	s_waitcnt vmcnt(3)
	v_mfma_f32_32x32x16_bf16 v[50:65], v[66:69], v[130:133], 0
	s_add_i32 s1, s1, 8
	s_cmp_gt_i32 s1, s34
	s_cselect_b64 s[2:3], -1, 0
	s_and_b64 vcc, exec, s[2:3]
	v_mfma_f32_32x32x16_bf16 v[34:49], v[82:85], v[130:133], 0
	v_mfma_f32_32x32x16_bf16 v[18:33], v[98:101], v[130:133], 0
	v_mfma_f32_32x32x16_bf16 v[2:17], v[114:117], v[130:133], 0
	global_load_dwordx4 v[130:133], v[210:211], off offset:-2048
	s_waitcnt vmcnt(3)
	v_mfma_f32_32x32x16_bf16 v[50:65], v[70:73], v[134:137], v[50:65]
	v_mfma_f32_32x32x16_bf16 v[34:49], v[86:89], v[134:137], v[34:49]
	v_mfma_f32_32x32x16_bf16 v[18:33], v[102:105], v[134:137], v[18:33]
	v_mfma_f32_32x32x16_bf16 v[2:17], v[118:121], v[134:137], v[2:17]
	global_load_dwordx4 v[134:137], v[210:211], off offset:-1024
	s_waitcnt vmcnt(3)
	v_mfma_f32_32x32x16_bf16 v[50:65], v[74:77], v[138:141], v[50:65]
	v_mfma_f32_32x32x16_bf16 v[34:49], v[90:93], v[138:141], v[34:49]
	v_mfma_f32_32x32x16_bf16 v[18:33], v[106:109], v[138:141], v[18:33]
	v_mfma_f32_32x32x16_bf16 v[2:17], v[122:125], v[138:141], v[2:17]
	global_load_dwordx4 v[138:141], v[210:211], off
	s_waitcnt vmcnt(3)
	v_mfma_f32_32x32x16_bf16 v[50:65], v[78:81], v[142:145], v[50:65]
	v_mfma_f32_32x32x16_bf16 v[34:49], v[94:97], v[142:145], v[34:49]
	v_mfma_f32_32x32x16_bf16 v[18:33], v[110:113], v[142:145], v[18:33]
	v_mfma_f32_32x32x16_bf16 v[2:17], v[126:129], v[142:145], v[2:17]
	global_load_dwordx4 v[142:145], v[210:211], off offset:1024
	s_branch .LBB0_332

.LBB0_779:
	s_cmp_le_i32 s76, s18
	s_cselect_b64 s[0:1], -1, 0
	s_and_b64 s[2:3], s[0:1], s[4:5]
	v_readlane_b32 s0, v236, 1
	s_mul_i32 s0, s0, 7
	s_add_i32 s29, s0, 6
	s_cmp_lt_i32 s29, s77
	s_cselect_b64 s[0:1], -1, 0
	s_andn2_b64 vcc, exec, s[2:3]
	s_cbranch_vccnz .LBB0_920
	v_readlane_b32 s98, v237, 48
	s_and_b32 s98, s98, 1
	s_cmp_eq_u32 s98, 0
	s_cbranch_scc1 .Lstg_skipp
	s_memrealtime s[98:99]
	s_waitcnt lgkmcnt(0)
	s_add_u32 s100, s98, 600
.Lstg_loopp:
	s_sleep 8
	s_memrealtime s[98:99]
	s_waitcnt lgkmcnt(0)
	s_sub_u32 s99, s100, s98
	s_cmp_gt_i32 s99, 0
	s_cbranch_scc1 .Lstg_loopp
.Lstg_skipp:
	v_readlane_b32 s2, v236, 1
	s_lshl_b32 s2, s2, 22
	v_readlane_b32 s3, v238, 27
	s_add_u32 s30, s3, s2
	v_readlane_b32 s2, v238, 28
	s_addc_u32 s31, s2, 0
	s_mov_b32 s4, 0
	s_branch .LBB0_783

	.amdhsa_kernel _Z14fwd_megakernel6Params
		.amdhsa_group_segment_fixed_size 0
		.amdhsa_private_segment_fixed_size 0
		.amdhsa_kernarg_size 376
		.amdhsa_user_sgpr_count 2
		.amdhsa_user_sgpr_dispatch_ptr 0
		.amdhsa_user_sgpr_queue_ptr 0
		.amdhsa_user_sgpr_kernarg_segment_ptr 1
		.amdhsa_user_sgpr_dispatch_id 0
		.amdhsa_user_sgpr_kernarg_preload_length 0
		.amdhsa_user_sgpr_kernarg_preload_offset 0
		.amdhsa_user_sgpr_private_segment_size 0
		.amdhsa_uses_dynamic_stack 0
		.amdhsa_enable_private_segment 0
		.amdhsa_system_sgpr_workgroup_id_x 1
		.amdhsa_system_sgpr_workgroup_id_y 0
		.amdhsa_system_sgpr_workgroup_id_z 0
		.amdhsa_system_sgpr_workgroup_info 0
		.amdhsa_system_vgpr_workitem_id 2
		.amdhsa_next_free_vgpr 256
		.amdhsa_next_free_sgpr 102
		.amdhsa_accum_offset 256
		.amdhsa_reserve_vcc 1
		.amdhsa_float_round_mode_32 0
		.amdhsa_float_round_mode_16_64 0
		.amdhsa_float_denorm_mode_32 3
		.amdhsa_float_denorm_mode_16_64 3
		.amdhsa_dx10_clamp 1
		.amdhsa_ieee_mode 1
		.amdhsa_fp16_overflow 0
		.amdhsa_tg_split 0
		.amdhsa_exception_fp_ieee_invalid_op 0
		.amdhsa_exception_fp_denorm_src 0
		.amdhsa_exception_fp_ieee_div_zero 0
		.amdhsa_exception_fp_ieee_overflow 0
		.amdhsa_exception_fp_ieee_underflow 0
		.amdhsa_exception_fp_ieee_inexact 0
		.amdhsa_exception_int_div_zero 0
	.end_amdhsa_kernel

amdhsa.kernels:
  - .agpr_count:     0
    .args:
      - .offset:         0
        .size:           120
        .value_kind:     by_value
      - .offset:         120
        .size:           4
        .value_kind:     hidden_block_count_x
      - .offset:         124
        .size:           4
        .value_kind:     hidden_block_count_y
      - .offset:         128
        .size:           4
        .value_kind:     hidden_block_count_z
      - .offset:         132
        .size:           2
        .value_kind:     hidden_group_size_x
      - .offset:         134
        .size:           2
        .value_kind:     hidden_group_size_y
      - .offset:         136
        .size:           2
        .value_kind:     hidden_group_size_z
      - .offset:         138
        .size:           2
        .value_kind:     hidden_remainder_x
      - .offset:         140
        .size:           2
        .value_kind:     hidden_remainder_y
      - .offset:         142
        .size:           2
        .value_kind:     hidden_remainder_z
      - .offset:         160
        .size:           8
        .value_kind:     hidden_global_offset_x
      - .offset:         168
        .size:           8
        .value_kind:     hidden_global_offset_y
      - .offset:         176
        .size:           8
        .value_kind:     hidden_global_offset_z
      - .offset:         184
        .size:           2
        .value_kind:     hidden_grid_dims
      - .offset:         208
        .size:           8
        .value_kind:     hidden_multigrid_sync_arg
      - .offset:         240
        .size:           4
        .value_kind:     hidden_dynamic_lds_size
    .group_segment_fixed_size: 0
    .kernarg_segment_align: 8
    .kernarg_segment_size: 376
    .language:       OpenCL C
    .language_version:
      - 2
      - 0
    .max_flat_workgroup_size: 512
    .name:           _Z14fwd_megakernel6Params
    .private_segment_fixed_size: 0
    .sgpr_count:     108
    .sgpr_spill_count: 375
    .symbol:         _Z14fwd_megakernel6Params.kd
    .uniform_work_group_size: 1
    .uses_dynamic_stack: false
    .vgpr_count:     256
    .vgpr_spill_count: 0
    .wavefront_size: 64
